# snake MFMA order; per-block setprio flips replaced by one static s_setprio 1 for waves 4-7 per GEMM phase (strategy lever 4)
# speedup vs baseline: 1.0035x; 1.0035x over previous
.LBB0_127:
	s_or_b64 exec, exec, s[34:35]
	s_cmp_lt_i32 s58, 2
	s_cselect_b64 s[0:1], -1, 0
	s_add_i32 s2, 0, 0x23fcc
	v_mov_b32_e32 v0, s2
	s_waitcnt lgkmcnt(0)
	s_barrier
	ds_read_b32 v0, v0
	s_and_b64 s[6:7], s[0:1], s[30:31]
	s_andn2_b64 vcc, exec, s[6:7]
	s_waitcnt lgkmcnt(0)
	v_readfirstlane_b32 s84, v0
	s_cbranch_vccnz .LBB0_149
	v_readfirstlane_b32 s3, v220
	s_movk_i32 s0, 0x800
	s_cmpk_gt_i32 s84, 0xaff
	s_cbranch_scc1 .LBB0_149
	v_lshrrev_b32_e32 v0, 5, v220
	v_lshrrev_b32_e32 v2, 1, v220
	v_and_b32_e32 v0, 4, v0
	v_bfe_u32 v1, v220, 2, 2
	v_and_b32_e32 v17, 24, v2
	v_or3_b32 v0, v0, v1, v17
	v_lshlrev_b32_e32 v1, 4, v220
	v_add_u32_e32 v2, 0x2000, v1
	v_lshrrev_b32_e32 v2, 7, v2
	v_and_b32_e32 v4, 32, v220
	s_add_u32 s24, s56, 0x8200000
	s_movk_i32 s2, 0xe0
	v_bitop3_b32 v12, v1, v4, 48 bitop3:0x6c
	v_and_b32_e32 v13, 64, v220
	v_and_b32_e32 v14, 0xf0, v2
	v_bfe_u32 v15, v220, 2, 4
	s_addc_u32 s25, s57, 0
	v_and_or_b32 v3, v2, s2, v0
	v_or_b32_e32 v1, v12, v13
	v_or_b32_e32 v2, v14, v15
	s_add_u32 s26, s56, 0x100000
	v_lshrrev_b32_e32 v1, 1, v1
	v_mul_lo_u32 v2, s0, v2
	s_addc_u32 s27, s57, 0
	v_add_lshl_u32 v130, v2, v1, 1
	v_lshrrev_b32_e32 v2, 3, v220
	s_movk_i32 s2, 0x60
	s_ashr_i32 s29, s84, 31
	v_and_or_b32 v0, v2, s2, v0
	s_lshr_b32 s2, s29, 29
	s_add_i32 s2, s84, s2
	s_lshr_b32 s4, s3, 6
	s_ashr_i32 s1, s0, 31
	s_ashr_i32 s12, s2, 3
	s_and_b32 s2, s2, -8
	s_lshr_b32 s5, s3, 8
	s_lshl_b64 s[8:9], s[0:1], 9
	s_lshl_b64 s[10:11], s[0:1], 8
	s_lshl_b32 s28, s4, 10
	s_sub_i32 s2, s84, s2
	s_cmp_lt_i32 s2, 0
	s_movk_i32 s30, 0x161
	s_cselect_b32 s13, s30, 0x160
	s_mul_i32 s2, s2, s13
	s_add_i32 s2, s2, s12
	s_mul_hi_i32 s12, s2, 0x2e8ba2e9
	s_lshr_b32 s13, s12, 31
	s_ashr_i32 s12, s12, 6
	s_add_i32 s12, s12, s13
	s_lshl_b32 s13, s12, 3
	s_mulk_i32 s12, 0x160
	s_sub_i32 s12, s2, s12
	s_bfe_u32 s2, s12, 0x3001c
	s_add_i32 s14, s12, s2
	s_sext_i32_i16 s16, s14
	s_and_b32 s14, s14, 0xfff8
	s_sub_i32 s12, s12, s14
	s_sext_i32_i16 s12, s12
	s_add_i32 s50, s13, s12
	s_ashr_i32 s12, s50, 31
	s_mul_i32 s12, s8, s12
	s_mul_hi_u32 s13, s8, s50
	s_add_i32 s14, s13, s12
	s_lshr_b64 s[12:13], s[0:1], 23
	s_lshr_b32 s2, s16, 3
	s_mul_i32 s13, s12, s50
	s_add_i32 s17, s14, s13
	s_bfe_i64 s[14:15], s[2:3], 0x100000
	s_ashr_i32 s13, s16, 3
	s_mul_hi_u32 s14, s8, s13
	s_mul_i32 s15, s8, s15
	s_add_i32 s14, s14, s15
	s_mul_i32 s12, s12, s13
	s_add_i32 s14, s14, s12
	s_mul_i32 s12, s8, s13
	s_add_u32 s22, s26, s12
	v_mul_lo_u32 v0, s0, v0
	s_addc_u32 s23, s27, s14
	s_add_i32 s31, s28, 0
	v_add_lshl_u32 v132, v0, v1, 1
	s_add_i32 m0, s31, 0x10000
	v_mul_lo_u32 v3, s0, v3
	global_load_lds_dwordx4 v132, s[22:23]
	s_add_i32 m0, s31, 0x12000
	v_add_lshl_u32 v128, v3, v1, 1
	s_add_u32 s12, s22, s10
	global_load_lds_dwordx4 v128, s[22:23]
	s_addc_u32 s13, s23, s11
	s_add_i32 m0, s31, 0x14000
	v_and_b32_e32 v16, 0x70, v2
	s_mul_i32 s18, s8, s50
	global_load_lds_dwordx4 v132, s[12:13]
	s_add_i32 m0, s31, 0x16000
	v_or_b32_e32 v0, v16, v15
	s_add_u32 s20, s24, s18
	v_mul_lo_u32 v0, s0, v0
	s_addc_u32 s21, s25, s17
	s_add_i32 s33, s31, 0x2000
	v_add_lshl_u32 v134, v0, v1, 1
	global_load_lds_dwordx4 v128, s[12:13]
	s_mov_b32 m0, s31
	s_add_u32 s14, s20, s10
	global_load_lds_dwordx4 v134, s[20:21]
	s_mov_b32 m0, s33
	s_addc_u32 s15, s21, s11
	s_add_i32 s34, s31, 0x4000
	global_load_lds_dwordx4 v130, s[20:21]
	s_mov_b32 m0, s34
	s_add_i32 s35, s31, 0x6000
	global_load_lds_dwordx4 v134, s[14:15]
	s_mov_b32 m0, s35
	v_mov_b32_e32 v137, 0
	global_load_lds_dwordx4 v130, s[14:15]
	v_mov_b32_e32 v133, v137
	v_mov_b32_e32 v129, v137
	v_mov_b32_e32 v135, v137
	v_mov_b32_e32 v131, v137
	s_cmp_eq_u32 s5, 1
	s_mov_b32 s36, 0
	v_lshl_add_u64 v[8:9], s[22:23], 0, v[132:133]
	v_lshl_add_u64 v[4:5], s[22:23], 0, v[128:129]
	v_lshl_add_u64 v[2:3], s[12:13], 0, v[132:133]
	v_lshl_add_u64 v[0:1], s[12:13], 0, v[128:129]
	v_lshl_add_u64 v[6:7], s[20:21], 0, v[134:135]
	s_cselect_b64 s[12:13], -1, 0
	s_cmp_lg_u32 s5, 1
	v_lshl_add_u64 v[10:11], s[20:21], 0, v[130:131]
	s_cbranch_scc1 .LBB0_131
	s_setprio 1
	s_barrier

.LBB0_149:
	s_setprio 0
	s_cmp_gt_i32 s59, 2
	s_cselect_b64 s[0:1], -1, 0
	s_and_b64 s[2:3], s[6:7], s[0:1]
	s_andn2_b64 vcc, exec, s[2:3]
	s_cbranch_vccnz .LBB0_203
	s_waitcnt vmcnt(0) lgkmcnt(0)
	s_waitcnt vmcnt(0)
	s_waitcnt vmcnt(0) lgkmcnt(0)
	s_barrier
	s_and_saveexec_b64 s[2:3], s[92:93]
	s_cbranch_execz .LBB0_202
	s_add_i32 s4, 0, 0x23fc0
	v_mov_b32_e32 v0, s4
	s_waitcnt vmcnt(0) expcnt(0) lgkmcnt(0)
	ds_read_b32 v2, v0
	s_add_i32 s4, 0, 0x23fc4
	v_mov_b32_e32 v0, s4
	ds_read_b32 v0, v0
	s_waitcnt lgkmcnt(1)
	v_cmp_ne_u32_e32 vcc, 0, v2
	s_cbranch_vccnz .LBB0_166
	s_add_u32 s4, s56, 0x21280200
	s_addc_u32 s5, s57, 0
	s_add_u32 s6, s56, 0x21280400
	s_addc_u32 s7, s57, 0
	s_add_u32 s8, s56, 0x21280500
	s_addc_u32 s9, s57, 0
	s_add_u32 s10, s56, 0x21280600
	s_addc_u32 s11, s57, 0
	s_add_u32 s12, s56, 0x21280700
	s_addc_u32 s13, s57, 0
	s_add_u32 s14, s56, 0x21280800
	s_addc_u32 s15, s57, 0
	s_add_u32 s16, s56, 0x21280900
	s_addc_u32 s17, s57, 0
	s_add_u32 s18, s56, 0x21280a00
	s_addc_u32 s19, s57, 0
	s_add_u32 s20, s56, 0x21280b00
	s_addc_u32 s21, s57, 0
	s_add_u32 s22, s56, 0x21280c00
	s_addc_u32 s23, s57, 0
	s_add_u32 s24, s56, 0x21280d00
	s_addc_u32 s25, s57, 0
	s_add_u32 s26, s56, 0x21280e00
	s_addc_u32 s27, s57, 0
	s_add_u32 s28, s56, 0x21280f00
	s_addc_u32 s29, s57, 0
	s_add_u32 s30, s56, 0x21281000
	s_addc_u32 s31, s57, 0
	s_add_u32 s34, s56, 0x21281100
	s_addc_u32 s35, s57, 0
	s_add_u32 s36, s56, 0x21281200
	s_addc_u32 s37, s57, 0
	s_mul_i32 s33, s91, s85
	s_add_u32 s38, s56, 0x21281300
	s_mul_i32 s33, s33, s90
	s_addc_u32 s39, s57, 0
	s_mov_b32 s46, 1
	v_mov_b32_e32 v16, 0
	s_branch .LBB0_154

.LBB0_210:
	s_andn2_b64 vcc, exec, s[4:5]
	s_cbranch_vccnz .LBB0_252
	s_add_u32 s33, s56, 0xc200000
	s_addc_u32 s34, s57, 0
	s_add_u32 s35, s56, 0x2d00000
	s_addc_u32 s36, s57, 0
	s_ashr_i32 s1, s0, 31
	s_lshl_b64 s[8:9], s[0:1], 9
	s_ashr_i32 s6, s54, 31
	s_mul_i32 s6, s8, s6
	s_mul_hi_u32 s7, s8, s54
	s_add_i32 s10, s7, s6
	s_lshr_b64 s[6:7], s[0:1], 23
	s_mul_i32 s7, s6, s54
	s_add_i32 s10, s10, s7
	s_ashr_i32 s7, s55, 31
	s_mul_i32 s7, s8, s7
	s_mul_hi_u32 s12, s8, s55
	s_lshr_b32 s5, s18, 6
	s_add_i32 s7, s12, s7
	s_mul_i32 s6, s6, s55
	s_lshr_b32 s4, s18, 8
	v_lshlrev_b32_e32 v3, 4, v220
	v_and_b32_e32 v0, 32, v220
	v_lshlrev_b32_e32 v2, 5, v220
	s_lshl_b32 s37, s5, 10
	s_add_i32 s7, s7, s6
	s_mul_i32 s6, s8, s55
	v_bitop3_b32 v0, v3, v0, 48 bitop3:0x6c
	v_and_b32_e32 v1, 64, v220
	v_and_b32_e32 v2, 0x780, v2
	s_add_u32 s26, s35, s6
	v_or3_b32 v5, v2, v1, v0
	v_and_b32_e32 v4, 0x3800, v3
	s_addc_u32 s27, s36, s7
	s_add_i32 s38, s37, 0
	v_or_b32_e32 v128, v5, v4
	v_add_u32_e32 v3, 0x2000, v3
	s_add_i32 m0, s38, 0x10000
	v_and_b32_e32 v3, 0x7800, v3
	global_load_lds_dwordx4 v128, s[26:27]
	s_add_i32 m0, s38, 0x12000
	v_or_b32_e32 v130, v5, v3
	s_add_u32 s6, s26, 0x4000
	global_load_lds_dwordx4 v130, s[26:27]
	s_addc_u32 s7, s27, 0
	s_add_i32 m0, s38, 0x14000
	s_mul_i32 s11, s8, s54
	global_load_lds_dwordx4 v128, s[6:7]
	s_add_i32 m0, s38, 0x16000
	s_add_u32 s24, s33, s11
	s_addc_u32 s25, s34, s10
	s_add_i32 s39, s38, 0x2000
	global_load_lds_dwordx4 v130, s[6:7]
	s_mov_b32 m0, s38
	s_add_u32 s6, s24, 0x4000
	global_load_lds_dwordx4 v128, s[24:25]
	s_mov_b32 m0, s39
	s_addc_u32 s7, s25, 0
	s_add_i32 s40, s38, 0x4000
	global_load_lds_dwordx4 v130, s[24:25]
	s_mov_b32 m0, s40
	s_add_i32 s41, s38, 0x6000
	global_load_lds_dwordx4 v128, s[6:7]
	s_mov_b32 m0, s41
	v_mov_b32_e32 v129, 0
	global_load_lds_dwordx4 v130, s[6:7]
	s_cmp_eq_u32 s4, 1
	s_mov_b32 s42, 0
	s_cselect_b64 s[10:11], -1, 0
	s_cmp_lg_u32 s4, 1
	v_mov_b32_e32 v131, v129
	s_cbranch_scc1 .LBB0_213
	s_setprio 1
	s_barrier

.LBB0_252:
	s_setprio 0
	s_cmp_gt_i32 s59, 3
	s_cselect_b64 s[0:1], -1, 0
	s_and_b64 s[2:3], s[2:3], s[0:1]
	s_andn2_b64 vcc, exec, s[2:3]
	s_cbranch_vccnz .LBB0_306
	s_waitcnt vmcnt(0) lgkmcnt(0)
	s_waitcnt vmcnt(0)
	s_waitcnt vmcnt(0) lgkmcnt(0)
	s_barrier
	s_and_saveexec_b64 s[2:3], s[92:93]
	s_cbranch_execz .LBB0_305
	s_add_i32 s4, 0, 0x23fc0
	v_mov_b32_e32 v0, s4
	s_waitcnt vmcnt(0) expcnt(0) lgkmcnt(0)
	ds_read_b32 v2, v0
	s_add_i32 s4, 0, 0x23fc4
	v_mov_b32_e32 v0, s4
	ds_read_b32 v0, v0
	s_waitcnt lgkmcnt(1)
	v_cmp_ne_u32_e32 vcc, 0, v2
	s_cbranch_vccnz .LBB0_269
	s_add_u32 s4, s56, 0x21280200
	s_addc_u32 s5, s57, 0
	s_add_u32 s6, s56, 0x21280400
	s_addc_u32 s7, s57, 0
	s_add_u32 s8, s56, 0x21280500
	s_addc_u32 s9, s57, 0
	s_add_u32 s10, s56, 0x21280600
	s_addc_u32 s11, s57, 0
	s_add_u32 s12, s56, 0x21280700
	s_addc_u32 s13, s57, 0
	s_add_u32 s14, s56, 0x21280800
	s_addc_u32 s15, s57, 0
	s_add_u32 s16, s56, 0x21280900
	s_addc_u32 s17, s57, 0
	s_add_u32 s18, s56, 0x21280a00
	s_addc_u32 s19, s57, 0
	s_add_u32 s20, s56, 0x21280b00
	s_addc_u32 s21, s57, 0
	s_add_u32 s22, s56, 0x21280c00
	s_addc_u32 s23, s57, 0
	s_add_u32 s24, s56, 0x21280d00
	s_addc_u32 s25, s57, 0
	s_add_u32 s26, s56, 0x21280e00
	s_addc_u32 s27, s57, 0
	s_add_u32 s28, s56, 0x21280f00
	s_addc_u32 s29, s57, 0
	s_add_u32 s30, s56, 0x21281000
	s_addc_u32 s31, s57, 0
	s_add_u32 s34, s56, 0x21281100
	s_addc_u32 s35, s57, 0
	s_add_u32 s36, s56, 0x21281200
	s_addc_u32 s37, s57, 0
	s_mul_i32 s33, s91, s85
	s_add_u32 s38, s56, 0x21281300
	s_mul_i32 s33, s33, s90
	s_addc_u32 s39, s57, 0
	s_mov_b32 s46, 1
	v_mov_b32_e32 v16, 0
	s_branch .LBB0_257

.LBB0_309:
	s_andn2_b64 vcc, exec, s[4:5]
	s_cbranch_vccnz .LBB0_434
	v_writelane_b32 v252, s2, 48
	v_lshrrev_b32_e32 v2, 1, v220
	v_lshrrev_b32_e32 v3, 5, v220
	v_writelane_b32 v252, s3, 49
	v_writelane_b32 v252, s78, 50
	v_writelane_b32 v252, s80, 51
	v_writelane_b32 v252, s88, 52
	s_add_u32 s66, s56, 0x8200000
	v_lshlrev_b32_e32 v0, 4, v220
	v_writelane_b32 v252, s89, 53
	v_writelane_b32 v252, s76, 54
	s_waitcnt lgkmcnt(0)
	v_and_b32_e32 v1, 32, v220
	v_and_b32_e32 v2, 24, v2
	v_writelane_b32 v252, s77, 55
	v_writelane_b32 v252, s85, 56
	v_and_b32_e32 v3, 4, v3
	v_bfe_u32 v4, v220, 2, 2
	v_readlane_b32 s68, v252, 16
	s_addc_u32 s67, s57, 0
	v_bitop3_b32 v12, v0, v1, 48 bitop3:0x6c
	v_or3_b32 v2, v3, v4, v2
	v_lshrrev_b32_e32 v3, 3, v220
	s_movk_i32 s1, 0x60
	v_add_u32_e32 v0, 0x2000, v0
	v_readlane_b32 s69, v252, 17
	s_add_u32 s68, s56, 0x4300000
	v_and_b32_e32 v15, 0x70, v3
	v_and_or_b32 v3, v3, s1, v2
	v_lshrrev_b32_e32 v0, 7, v0
	s_movk_i32 s1, 0xe0
	s_addc_u32 s69, s57, 0
	v_and_b32_e32 v16, 0xf0, v0
	v_and_or_b32 v0, v0, s1, v2
	s_ashr_i32 s1, s0, 31
	s_lshr_b64 s[14:15], s[0:1], 23
	s_lshl_b64 s[8:9], s[0:1], 9
	s_ashr_i32 s7, s12, 31
	s_ashr_i32 s15, s89, 31
	s_mul_i32 s7, s8, s7
	s_mul_hi_u32 s13, s8, s12
	s_mul_i32 s15, s8, s15
	s_mul_hi_u32 s16, s8, s89
	v_readlane_b32 s70, v252, 18
	s_lshr_b32 s4, s6, 6
	s_add_i32 s7, s13, s7
	s_mul_i32 s13, s14, s12
	s_add_i32 s15, s16, s15
	s_mul_i32 s14, s14, s89
	v_and_b32_e32 v13, 64, v220
	s_lshr_b32 s5, s6, 8
	s_lshl_b64 s[10:11], s[0:1], 8
	s_lshl_b32 s70, s4, 10
	s_add_i32 s7, s7, s13
	s_add_i32 s15, s15, s14
	s_mul_i32 s14, s8, s89
	v_readlane_b32 s71, v252, 19
	v_or_b32_e32 v1, v12, v13
	s_add_u32 s50, s68, s14
	v_lshrrev_b32_e32 v1, 1, v1
	v_mul_lo_u32 v3, s0, v3
	s_addc_u32 s51, s69, s15
	s_add_i32 s71, s70, 0
	v_add_lshl_u32 v166, v3, v1, 1
	s_add_i32 m0, s71, 0x10000
	v_mul_lo_u32 v0, s0, v0
	global_load_lds_dwordx4 v166, s[50:51]
	s_add_i32 m0, s71, 0x12000
	v_add_lshl_u32 v170, v0, v1, 1
	s_add_u32 s14, s50, s10
	global_load_lds_dwordx4 v170, s[50:51]
	s_addc_u32 s15, s51, s11
	s_add_i32 m0, s71, 0x14000
	v_bfe_u32 v14, v220, 2, 4
	s_mul_i32 s13, s8, s12
	global_load_lds_dwordx4 v166, s[14:15]
	s_add_i32 m0, s71, 0x16000
	v_readlane_b32 s72, v252, 20
	v_or_b32_e32 v4, v15, v14
	s_add_u32 s52, s66, s13
	v_mul_lo_u32 v4, s0, v4
	v_or_b32_e32 v3, v16, v14
	s_addc_u32 s53, s67, s7
	s_add_i32 s72, s71, 0x2000
	v_readlane_b32 s73, v252, 21
	v_add_lshl_u32 v164, v4, v1, 1
	v_mul_lo_u32 v2, s0, v3
	global_load_lds_dwordx4 v170, s[14:15]
	s_mov_b32 m0, s71
	s_add_u32 s16, s52, s10
	v_readlane_b32 s74, v252, 22
	v_add_lshl_u32 v168, v2, v1, 1
	global_load_lds_dwordx4 v164, s[52:53]
	s_mov_b32 m0, s72
	s_addc_u32 s17, s53, s11
	s_add_i32 s73, s71, 0x4000
	global_load_lds_dwordx4 v168, s[52:53]
	s_mov_b32 m0, s73
	s_add_i32 s74, s71, 0x6000
	global_load_lds_dwordx4 v164, s[16:17]
	s_mov_b32 m0, s74
	v_mov_b32_e32 v173, 0
	global_load_lds_dwordx4 v168, s[16:17]
	v_mov_b32_e32 v167, v173
	v_mov_b32_e32 v171, v173
	v_mov_b32_e32 v165, v173
	v_mov_b32_e32 v169, v173
	s_cmp_eq_u32 s5, 1
	s_mov_b32 s13, 0
	v_lshl_add_u64 v[8:9], s[50:51], 0, v[166:167]
	v_lshl_add_u64 v[4:5], s[50:51], 0, v[170:171]
	v_lshl_add_u64 v[2:3], s[14:15], 0, v[166:167]
	v_lshl_add_u64 v[0:1], s[14:15], 0, v[170:171]
	v_lshl_add_u64 v[6:7], s[52:53], 0, v[164:165]
	s_cselect_b64 s[14:15], -1, 0
	s_cmp_lg_u32 s5, 1
	v_lshl_add_u64 v[10:11], s[52:53], 0, v[168:169]
	v_readlane_b32 s75, v252, 23
	v_readlane_b32 s76, v252, 24
	v_readlane_b32 s77, v252, 25
	v_readlane_b32 s78, v252, 26
	v_readlane_b32 s79, v252, 27
	v_readlane_b32 s80, v252, 28
	v_readlane_b32 s81, v252, 29
	v_readlane_b32 s82, v252, 30
	v_readlane_b32 s83, v252, 31
	s_cbranch_scc1 .LBB0_312
	s_setprio 1
	s_barrier

.LBB0_434:
	s_setprio 0
	s_cmp_gt_i32 s59, 4
	s_cselect_b64 s[0:1], -1, 0
	s_and_b64 s[2:3], s[2:3], s[0:1]
	v_readlane_b32 s36, v252, 0
	s_andn2_b64 vcc, exec, s[2:3]
	v_readlane_b32 s38, v252, 2
	v_readlane_b32 s39, v252, 3
	v_readlane_b32 s37, v252, 1
	v_readlane_b32 s40, v252, 4
	v_readlane_b32 s41, v252, 5
	v_readlane_b32 s42, v252, 6
	v_readlane_b32 s43, v252, 7
	v_readlane_b32 s44, v252, 8
	v_readlane_b32 s45, v252, 9
	v_readlane_b32 s46, v252, 10
	v_readlane_b32 s47, v252, 11
	v_readlane_b32 s48, v252, 12
	v_readlane_b32 s49, v252, 13
	v_readlane_b32 s50, v252, 14
	v_readlane_b32 s51, v252, 15
	s_cbranch_vccnz .LBB0_488
	s_waitcnt vmcnt(0) lgkmcnt(0)
	s_waitcnt vmcnt(0)
	s_waitcnt vmcnt(0) lgkmcnt(0)
	s_barrier
	s_and_saveexec_b64 s[2:3], s[92:93]
	s_cbranch_execz .LBB0_487
	s_add_i32 s4, 0, 0x23fc0
	v_mov_b32_e32 v0, s4
	s_waitcnt vmcnt(0) expcnt(0) lgkmcnt(0)
	ds_read_b32 v2, v0
	s_add_i32 s4, 0, 0x23fc4
	v_mov_b32_e32 v0, s4
	ds_read_b32 v0, v0
	s_waitcnt lgkmcnt(1)
	v_cmp_ne_u32_e32 vcc, 0, v2
	s_cbranch_vccnz .LBB0_451
	s_add_u32 s4, s56, 0x21280200
	s_addc_u32 s5, s57, 0
	s_add_u32 s6, s56, 0x21280400
	s_addc_u32 s7, s57, 0
	s_add_u32 s8, s56, 0x21280500
	s_addc_u32 s9, s57, 0
	s_add_u32 s10, s56, 0x21280600
	s_addc_u32 s11, s57, 0
	s_add_u32 s12, s56, 0x21280700
	s_addc_u32 s13, s57, 0
	s_add_u32 s14, s56, 0x21280800
	s_addc_u32 s15, s57, 0
	s_add_u32 s16, s56, 0x21280900
	s_addc_u32 s17, s57, 0
	s_add_u32 s18, s56, 0x21280a00
	s_addc_u32 s19, s57, 0
	s_add_u32 s20, s56, 0x21280b00
	s_addc_u32 s21, s57, 0
	s_add_u32 s22, s56, 0x21280c00
	s_addc_u32 s23, s57, 0
	s_add_u32 s24, s56, 0x21280d00
	s_addc_u32 s25, s57, 0
	s_add_u32 s26, s56, 0x21280e00
	s_addc_u32 s27, s57, 0
	s_add_u32 s28, s56, 0x21280f00
	s_addc_u32 s29, s57, 0
	s_add_u32 s30, s56, 0x21281000
	s_addc_u32 s31, s57, 0
	s_add_u32 s34, s56, 0x21281100
	s_addc_u32 s35, s57, 0
	s_add_u32 s36, s56, 0x21281200
	s_addc_u32 s37, s57, 0
	s_mul_i32 s33, s91, s85
	s_add_u32 s38, s56, 0x21281300
	s_mul_i32 s33, s33, s90
	s_addc_u32 s39, s57, 0
	s_mov_b32 s46, 1
	v_mov_b32_e32 v16, 0
	s_branch .LBB0_439

.LBB0_575:
	s_ashr_i32 s2, s1, 3
	s_add_u32 s36, s56, 0x8200000
	s_addc_u32 s37, s57, 0
	s_add_u32 s38, s56, 0x6900000
	s_addc_u32 s39, s57, 0
	s_add_i32 s2, s10, s2
	s_ashr_i32 s10, s2, 31
	s_lshr_b32 s10, s10, 26
	s_add_i32 s10, s2, s10
	s_ashr_i32 s11, s10, 6
	s_and_b32 s10, s10, 0xffc0
	s_sub_i32 s10, s2, s10
	s_bfe_i32 s2, s10, 0x80000
	v_lshrrev_b32_e32 v2, 1, v220
	s_bfe_u32 s2, s2, 0x3000c
	v_and_b32_e32 v16, 24, v2
	v_lshrrev_b32_e32 v2, 5, v220
	s_add_i32 s12, s10, s2
	v_lshlrev_b32_e32 v0, 4, v220
	v_and_b32_e32 v1, 32, v220
	v_and_b32_e32 v2, 4, v2
	v_bfe_u32 v3, v220, 2, 2
	s_bfe_i32 s2, s12, 0x80000
	s_and_b32 s12, s12, 0xf8
	v_bitop3_b32 v13, v0, v1, 48 bitop3:0x6c
	v_or3_b32 v2, v2, v3, v16
	v_lshrrev_b32_e32 v3, 3, v220
	s_movk_i32 s1, 0x60
	v_add_u32_e32 v0, 0x2000, v0
	s_sub_i32 s10, s10, s12
	v_and_b32_e32 v17, 0x70, v3
	v_and_or_b32 v3, v3, s1, v2
	v_lshrrev_b32_e32 v0, 7, v0
	s_movk_i32 s1, 0xe0
	s_lshl_b32 s11, s11, 3
	s_sext_i32_i8 s10, s10
	v_and_b32_e32 v18, 0xf0, v0
	v_and_or_b32 v0, v0, s1, v2
	s_ashr_i32 s1, s0, 31
	s_add_i32 s60, s11, s10
	s_lshl_b64 s[6:7], s[0:1], 9
	s_ashr_i32 s10, s60, 31
	s_mul_i32 s10, s6, s10
	s_mul_hi_u32 s11, s6, s60
	s_sext_i32_i16 s14, s2
	s_add_i32 s12, s11, s10
	s_lshr_b64 s[10:11], s[0:1], 23
	s_lshr_b32 s3, s18, 8
	s_lshr_b32 s2, s14, 3
	s_mul_i32 s11, s10, s60
	s_add_i32 s15, s12, s11
	s_bfe_i64 s[12:13], s[2:3], 0x100000
	s_ashr_i32 s11, s14, 3
	s_mul_hi_u32 s12, s6, s11
	s_mul_i32 s13, s6, s13
	s_lshr_b32 s16, s18, 6
	s_add_i32 s12, s12, s13
	s_mul_i32 s10, s10, s11
	v_and_b32_e32 v14, 64, v220
	s_lshl_b64 s[8:9], s[0:1], 8
	s_lshl_b32 s40, s16, 10
	s_add_i32 s12, s12, s10
	s_mul_i32 s10, s6, s11
	v_or_b32_e32 v1, v13, v14
	s_add_u32 s34, s38, s10
	v_lshrrev_b32_e32 v1, 1, v1
	v_mul_lo_u32 v3, s0, v3
	s_addc_u32 s35, s39, s12
	s_add_i32 s41, s40, 0
	v_add_lshl_u32 v130, v3, v1, 1
	s_add_i32 m0, s41, 0x10000
	v_mul_lo_u32 v0, s0, v0
	global_load_lds_dwordx4 v130, s[34:35]
	s_add_i32 m0, s41, 0x12000
	v_add_lshl_u32 v134, v0, v1, 1
	s_add_u32 s10, s34, s8
	global_load_lds_dwordx4 v134, s[34:35]
	s_addc_u32 s11, s35, s9
	s_add_i32 m0, s41, 0x14000
	v_bfe_u32 v15, v220, 2, 4
	s_mul_i32 s17, s6, s60
	global_load_lds_dwordx4 v130, s[10:11]
	s_add_i32 m0, s41, 0x16000
	v_or_b32_e32 v4, v17, v15
	s_add_u32 s30, s36, s17
	v_mul_lo_u32 v4, s0, v4
	v_or_b32_e32 v3, v18, v15
	s_addc_u32 s31, s37, s15
	s_add_i32 s42, s41, 0x2000
	v_add_lshl_u32 v128, v4, v1, 1
	v_mul_lo_u32 v2, s0, v3
	global_load_lds_dwordx4 v134, s[10:11]
	s_mov_b32 m0, s41
	s_add_u32 s12, s30, s8
	v_add_lshl_u32 v132, v2, v1, 1
	global_load_lds_dwordx4 v128, s[30:31]
	s_mov_b32 m0, s42
	s_addc_u32 s13, s31, s9
	s_add_i32 s43, s41, 0x4000
	global_load_lds_dwordx4 v132, s[30:31]
	s_mov_b32 m0, s43
	s_add_i32 s44, s41, 0x6000
	global_load_lds_dwordx4 v128, s[12:13]
	s_mov_b32 m0, s44
	v_mov_b32_e32 v131, 0
	global_load_lds_dwordx4 v132, s[12:13]
	v_mov_b32_e32 v135, v131
	v_mov_b32_e32 v129, v131
	v_mov_b32_e32 v133, v131
	s_cmp_eq_u32 s3, 1
	s_mov_b32 s45, 0
	v_lshl_add_u64 v[8:9], s[34:35], 0, v[130:131]
	v_lshl_add_u64 v[4:5], s[34:35], 0, v[134:135]
	v_lshl_add_u64 v[2:3], s[10:11], 0, v[130:131]
	v_lshl_add_u64 v[0:1], s[10:11], 0, v[134:135]
	v_lshl_add_u64 v[6:7], s[30:31], 0, v[128:129]
	s_cselect_b64 s[10:11], -1, 0
	s_cmp_lg_u32 s3, 1
	v_lshl_add_u64 v[10:11], s[30:31], 0, v[132:133]
	s_cbranch_scc1 .LBB0_577
	s_setprio 1
	s_barrier

.LBB0_599:
	s_setprio 0
	s_cmp_gt_i32 s59, 6
	s_cselect_b64 s[0:1], -1, 0
	s_and_b64 s[2:3], s[4:5], s[0:1]
	s_andn2_b64 vcc, exec, s[2:3]
	s_cbranch_vccnz .LBB0_653
	s_waitcnt vmcnt(0) lgkmcnt(0)
	s_waitcnt vmcnt(0)
	s_waitcnt vmcnt(0) lgkmcnt(0)
	s_barrier
	s_and_saveexec_b64 s[2:3], s[92:93]
	s_cbranch_execz .LBB0_652
	s_add_i32 s4, 0, 0x23fc0
	v_mov_b32_e32 v0, s4
	s_waitcnt vmcnt(0) expcnt(0) lgkmcnt(0)
	ds_read_b32 v2, v0
	s_add_i32 s4, 0, 0x23fc4
	v_mov_b32_e32 v0, s4
	ds_read_b32 v0, v0
	s_waitcnt lgkmcnt(1)
	v_cmp_ne_u32_e32 vcc, 0, v2
	s_cbranch_vccnz .LBB0_616
	s_add_u32 s4, s56, 0x21280200
	s_addc_u32 s5, s57, 0
	s_add_u32 s6, s56, 0x21280400
	s_addc_u32 s7, s57, 0
	s_add_u32 s8, s56, 0x21280500
	s_addc_u32 s9, s57, 0
	s_add_u32 s10, s56, 0x21280600
	s_addc_u32 s11, s57, 0
	s_add_u32 s12, s56, 0x21280700
	s_addc_u32 s13, s57, 0
	s_add_u32 s14, s56, 0x21280800
	s_addc_u32 s15, s57, 0
	s_add_u32 s16, s56, 0x21280900
	s_addc_u32 s17, s57, 0
	s_add_u32 s18, s56, 0x21280a00
	s_addc_u32 s19, s57, 0
	s_add_u32 s20, s56, 0x21280b00
	s_addc_u32 s21, s57, 0
	s_add_u32 s22, s56, 0x21280c00
	s_addc_u32 s23, s57, 0
	s_add_u32 s24, s56, 0x21280d00
	s_addc_u32 s25, s57, 0
	s_add_u32 s26, s56, 0x21280e00
	s_addc_u32 s27, s57, 0
	s_add_u32 s28, s56, 0x21280f00
	s_addc_u32 s29, s57, 0
	s_add_u32 s30, s56, 0x21281000
	s_addc_u32 s31, s57, 0
	s_add_u32 s34, s56, 0x21281100
	s_addc_u32 s35, s57, 0
	s_add_u32 s36, s56, 0x21281200
	s_addc_u32 s37, s57, 0
	s_mul_i32 s33, s91, s85
	s_add_u32 s38, s56, 0x21281300
	s_mul_i32 s33, s33, s90
	s_addc_u32 s39, s57, 0
	s_mov_b32 s46, 1
	v_mov_b32_e32 v16, 0
	s_branch .LBB0_604

.LBB0_746:
	s_ashr_i32 s2, s1, 3
	s_add_u32 s29, s56, 0xa200000
	s_addc_u32 s30, s57, 0
	s_add_u32 s31, s56, 0x6d00000
	s_addc_u32 s33, s57, 0
	s_add_i32 s2, s10, s2
	s_ashr_i32 s10, s2, 31
	s_lshr_b32 s10, s10, 26
	s_add_i32 s10, s2, s10
	s_ashr_i32 s11, s10, 6
	s_and_b32 s10, s10, 0xffc0
	s_sub_i32 s10, s2, s10
	s_bfe_i32 s2, s10, 0x80000
	v_lshrrev_b32_e32 v2, 1, v220
	s_bfe_u32 s2, s2, 0x3000c
	v_and_b32_e32 v15, 24, v2
	v_lshrrev_b32_e32 v2, 5, v220
	s_add_i32 s12, s10, s2
	v_lshlrev_b32_e32 v0, 4, v220
	v_and_b32_e32 v1, 32, v220
	v_and_b32_e32 v2, 4, v2
	v_bfe_u32 v3, v220, 2, 2
	s_bfe_i32 s2, s12, 0x80000
	s_and_b32 s12, s12, 0xf8
	v_bitop3_b32 v12, v0, v1, 48 bitop3:0x6c
	v_or3_b32 v2, v2, v3, v15
	v_lshrrev_b32_e32 v3, 3, v220
	s_movk_i32 s1, 0x60
	v_add_u32_e32 v0, 0x2000, v0
	s_sub_i32 s10, s10, s12
	v_and_b32_e32 v16, 0x70, v3
	v_and_or_b32 v3, v3, s1, v2
	v_lshrrev_b32_e32 v0, 7, v0
	s_movk_i32 s1, 0xe0
	s_lshl_b32 s11, s11, 3
	s_sext_i32_i8 s10, s10
	v_and_b32_e32 v17, 0xf0, v0
	v_and_or_b32 v0, v0, s1, v2
	s_ashr_i32 s1, s0, 31
	s_add_i32 s50, s11, s10
	s_lshl_b64 s[6:7], s[0:1], 9
	s_ashr_i32 s10, s50, 31
	s_mul_i32 s10, s6, s10
	s_mul_hi_u32 s11, s6, s50
	s_sext_i32_i16 s14, s2
	s_add_i32 s12, s11, s10
	s_lshr_b64 s[10:11], s[0:1], 23
	s_lshr_b32 s3, s20, 8
	s_lshr_b32 s2, s14, 3
	s_mul_i32 s11, s10, s50
	s_add_i32 s15, s12, s11
	s_bfe_i64 s[12:13], s[2:3], 0x100000
	s_ashr_i32 s11, s14, 3
	s_mul_hi_u32 s12, s6, s11
	s_mul_i32 s13, s6, s13
	s_lshr_b32 s18, s20, 6
	s_add_i32 s12, s12, s13
	s_mul_i32 s10, s10, s11
	v_and_b32_e32 v13, 64, v220
	s_lshl_b64 s[8:9], s[0:1], 8
	s_lshl_b32 s34, s18, 10
	s_add_i32 s12, s12, s10
	s_mul_i32 s10, s6, s11
	v_or_b32_e32 v1, v12, v13
	s_add_u32 s26, s31, s10
	v_lshrrev_b32_e32 v1, 1, v1
	v_mul_lo_u32 v3, s0, v3
	s_addc_u32 s27, s33, s12
	s_add_i32 s35, s34, 0
	v_add_lshl_u32 v154, v3, v1, 1
	s_add_i32 m0, s35, 0x10000
	v_mul_lo_u32 v0, s0, v0
	global_load_lds_dwordx4 v154, s[26:27]
	s_add_i32 m0, s35, 0x12000
	v_add_lshl_u32 v158, v0, v1, 1
	s_add_u32 s10, s26, s8
	global_load_lds_dwordx4 v158, s[26:27]
	s_addc_u32 s11, s27, s9
	s_add_i32 m0, s35, 0x14000
	v_bfe_u32 v14, v220, 2, 4
	s_mul_i32 s16, s6, s50
	global_load_lds_dwordx4 v154, s[10:11]
	s_add_i32 m0, s35, 0x16000
	v_or_b32_e32 v4, v16, v14
	s_add_u32 s24, s29, s16
	v_mul_lo_u32 v4, s0, v4
	v_or_b32_e32 v3, v17, v14
	s_addc_u32 s25, s30, s15
	s_add_i32 s36, s35, 0x2000
	v_add_lshl_u32 v152, v4, v1, 1
	v_mul_lo_u32 v2, s0, v3
	global_load_lds_dwordx4 v158, s[10:11]
	s_mov_b32 m0, s35
	s_add_u32 s12, s24, s8
	v_add_lshl_u32 v156, v2, v1, 1
	global_load_lds_dwordx4 v152, s[24:25]
	s_mov_b32 m0, s36
	s_addc_u32 s13, s25, s9
	s_add_i32 s37, s35, 0x4000
	global_load_lds_dwordx4 v156, s[24:25]
	s_mov_b32 m0, s37
	s_add_i32 s38, s35, 0x6000
	global_load_lds_dwordx4 v152, s[12:13]
	s_mov_b32 m0, s38
	v_mov_b32_e32 v155, 0
	global_load_lds_dwordx4 v156, s[12:13]
	v_mov_b32_e32 v159, v155
	v_mov_b32_e32 v153, v155
	v_mov_b32_e32 v157, v155
	s_cmp_eq_u32 s3, 1
	s_mov_b32 s39, 0
	v_lshl_add_u64 v[8:9], s[26:27], 0, v[154:155]
	v_lshl_add_u64 v[4:5], s[26:27], 0, v[158:159]
	v_lshl_add_u64 v[2:3], s[10:11], 0, v[154:155]
	v_lshl_add_u64 v[0:1], s[10:11], 0, v[158:159]
	v_lshl_add_u64 v[6:7], s[24:25], 0, v[152:153]
	s_cselect_b64 s[10:11], -1, 0
	s_cmp_lg_u32 s3, 1
	v_lshl_add_u64 v[10:11], s[24:25], 0, v[156:157]
	s_cbranch_scc1 .LBB0_748
	s_setprio 1
	s_barrier

.LBB0_770:
	s_setprio 0
	s_cmp_gt_i32 s59, 8
	s_cselect_b64 s[0:1], -1, 0
	s_and_b64 s[2:3], s[4:5], s[0:1]
	s_andn2_b64 vcc, exec, s[2:3]
	s_cbranch_vccnz .LBB0_824
	s_waitcnt vmcnt(0) lgkmcnt(0)
	s_waitcnt vmcnt(0)
	s_waitcnt vmcnt(0) lgkmcnt(0)
	s_barrier
	s_and_saveexec_b64 s[2:3], s[92:93]
	s_cbranch_execz .LBB0_823
	s_add_i32 s4, 0, 0x23fc0
	v_mov_b32_e32 v0, s4
	s_waitcnt vmcnt(0) expcnt(0) lgkmcnt(0)
	ds_read_b32 v2, v0
	s_add_i32 s4, 0, 0x23fc4
	v_mov_b32_e32 v0, s4
	ds_read_b32 v0, v0
	s_waitcnt lgkmcnt(1)
	v_cmp_ne_u32_e32 vcc, 0, v2
	s_cbranch_vccnz .LBB0_787
	s_add_u32 s4, s56, 0x21280200
	s_addc_u32 s5, s57, 0
	s_add_u32 s6, s56, 0x21280400
	s_addc_u32 s7, s57, 0
	s_add_u32 s8, s56, 0x21280500
	s_addc_u32 s9, s57, 0
	s_add_u32 s10, s56, 0x21280600
	s_addc_u32 s11, s57, 0
	s_add_u32 s12, s56, 0x21280700
	s_addc_u32 s13, s57, 0
	s_add_u32 s14, s56, 0x21280800
	s_addc_u32 s15, s57, 0
	s_add_u32 s16, s56, 0x21280900
	s_addc_u32 s17, s57, 0
	s_add_u32 s18, s56, 0x21280a00
	s_addc_u32 s19, s57, 0
	s_add_u32 s20, s56, 0x21280b00
	s_addc_u32 s21, s57, 0
	s_add_u32 s22, s56, 0x21280c00
	s_addc_u32 s23, s57, 0
	s_add_u32 s24, s56, 0x21280d00
	s_addc_u32 s25, s57, 0
	s_add_u32 s26, s56, 0x21280e00
	s_addc_u32 s27, s57, 0
	s_add_u32 s28, s56, 0x21280f00
	s_addc_u32 s29, s57, 0
	s_add_u32 s30, s56, 0x21281000
	s_addc_u32 s31, s57, 0
	s_add_u32 s34, s56, 0x21281100
	s_addc_u32 s35, s57, 0
	s_add_u32 s36, s56, 0x21281200
	s_addc_u32 s37, s57, 0
	s_mul_i32 s33, s91, s85
	s_add_u32 s38, s56, 0x21281300
	s_mul_i32 s33, s33, s90
	s_addc_u32 s39, s57, 0
	s_mov_b32 s46, 1
	v_mov_b32_e32 v16, 0
	s_branch .LBB0_775

.LBB0_831:
	s_andn2_b64 vcc, exec, s[2:3]
	s_cbranch_vccnz .LBB0_872
	s_add_u32 s33, s56, 0x19200000
	s_addc_u32 s34, s57, 0
	s_waitcnt lgkmcnt(0)
	v_lshlrev_b32_e32 v1, 4, v220
	v_and_b32_e32 v0, 32, v220
	v_lshrrev_b32_e32 v2, 3, v220
	s_add_u32 s35, s56, 0x7100000
	v_bfe_u32 v14, v220, 2, 4
	v_bitop3_b32 v12, v1, v0, 48 bitop3:0x6c
	v_and_b32_e32 v13, 64, v220
	v_and_b32_e32 v16, 0x70, v2
	s_addc_u32 s36, s57, 0
	v_or_b32_e32 v0, v12, v13
	s_lshl_b32 s1, s0, 1
	v_or_b32_e32 v2, v16, v14
	v_mad_u64_u32 v[176:177], s[4:5], s1, v2, v[0:1]
	v_add_u32_e32 v1, 0x2000, v1
	v_lshrrev_b32_e32 v1, 7, v1
	v_and_b32_e32 v15, 0xf0, v1
	v_or_b32_e32 v1, v15, v14
	v_mad_u64_u32 v[178:179], s[4:5], s1, v1, v[0:1]
	s_ashr_i32 s1, s0, 31
	s_lshl_b64 s[8:9], s[0:1], 9
	s_ashr_i32 s4, s54, 31
	s_mul_i32 s4, s8, s4
	s_mul_hi_u32 s5, s8, s54
	s_add_i32 s12, s5, s4
	s_lshr_b64 s[4:5], s[0:1], 23
	s_mul_i32 s5, s4, s54
	s_add_i32 s12, s12, s5
	s_ashr_i32 s5, s55, 31
	s_mul_i32 s5, s8, s5
	s_mul_hi_u32 s14, s8, s55
	s_lshr_b32 s3, s22, 6
	s_add_i32 s5, s14, s5
	s_mul_i32 s4, s4, s55
	s_lshr_b32 s2, s22, 8
	s_lshl_b64 s[10:11], s[0:1], 8
	s_lshl_b32 s37, s3, 10
	s_add_i32 s5, s5, s4
	s_mul_i32 s4, s8, s55
	s_add_u32 s30, s35, s4
	s_addc_u32 s31, s36, s5
	s_add_i32 s38, s37, 0
	s_add_i32 m0, s38, 0x10000
	s_mul_i32 s13, s8, s54
	global_load_lds_dwordx4 v176, s[30:31]
	s_add_i32 m0, s38, 0x12000
	s_add_u32 s4, s30, s10
	global_load_lds_dwordx4 v178, s[30:31]
	s_addc_u32 s5, s31, s11
	s_add_i32 m0, s38, 0x14000
	v_mov_b32_e32 v177, 0
	global_load_lds_dwordx4 v176, s[4:5]
	s_add_i32 m0, s38, 0x16000
	s_add_u32 s28, s33, s13
	s_addc_u32 s29, s34, s12
	s_add_i32 s39, s38, 0x2000
	global_load_lds_dwordx4 v178, s[4:5]
	s_mov_b32 m0, s38
	s_add_u32 s12, s28, s10
	global_load_lds_dwordx4 v176, s[28:29]
	s_mov_b32 m0, s39
	s_addc_u32 s13, s29, s11
	s_add_i32 s40, s38, 0x4000
	global_load_lds_dwordx4 v178, s[28:29]
	s_mov_b32 m0, s40
	s_add_i32 s41, s38, 0x6000
	global_load_lds_dwordx4 v176, s[12:13]
	s_mov_b32 m0, s41
	v_mov_b32_e32 v179, v177
	global_load_lds_dwordx4 v178, s[12:13]
	s_cmp_eq_u32 s2, 1
	s_mov_b32 s42, 0
	v_lshl_add_u64 v[10:11], s[30:31], 0, v[176:177]
	v_lshl_add_u64 v[8:9], s[30:31], 0, v[178:179]
	v_lshl_add_u64 v[2:3], s[4:5], 0, v[176:177]
	v_lshl_add_u64 v[0:1], s[4:5], 0, v[178:179]
	v_lshl_add_u64 v[4:5], s[28:29], 0, v[176:177]
	s_cselect_b64 s[12:13], -1, 0
	s_cmp_lg_u32 s2, 1
	v_lshl_add_u64 v[6:7], s[28:29], 0, v[178:179]
	s_cbranch_scc1 .LBB0_834
	s_setprio 1
	s_barrier

.LBB0_872:
	s_setprio 0
	s_cmp_gt_i32 s59, 9
	s_cselect_b64 s[0:1], -1, 0
	s_and_b64 s[2:3], s[6:7], s[0:1]
	s_andn2_b64 vcc, exec, s[2:3]
	s_cbranch_vccnz .LBB0_926
	s_waitcnt vmcnt(0) lgkmcnt(0)
	s_waitcnt vmcnt(0)
	s_waitcnt vmcnt(0) lgkmcnt(0)
	s_barrier
	s_and_saveexec_b64 s[2:3], s[92:93]
	s_cbranch_execz .LBB0_925
	s_add_i32 s4, 0, 0x23fc0
	v_mov_b32_e32 v0, s4
	s_waitcnt vmcnt(0) expcnt(0) lgkmcnt(0)
	ds_read_b32 v2, v0
	s_add_i32 s4, 0, 0x23fc4
	v_mov_b32_e32 v0, s4
	ds_read_b32 v0, v0
	s_waitcnt lgkmcnt(1)
	v_cmp_ne_u32_e32 vcc, 0, v2
	s_cbranch_vccnz .LBB0_889
	s_add_u32 s4, s56, 0x21280200
	s_addc_u32 s5, s57, 0
	s_add_u32 s6, s56, 0x21280400
	s_addc_u32 s7, s57, 0
	s_add_u32 s8, s56, 0x21280500
	s_addc_u32 s9, s57, 0
	s_add_u32 s10, s56, 0x21280600
	s_addc_u32 s11, s57, 0
	s_add_u32 s12, s56, 0x21280700
	s_addc_u32 s13, s57, 0
	s_add_u32 s14, s56, 0x21280800
	s_addc_u32 s15, s57, 0
	s_add_u32 s16, s56, 0x21280900
	s_addc_u32 s17, s57, 0
	s_add_u32 s18, s56, 0x21280a00
	s_addc_u32 s19, s57, 0
	s_add_u32 s20, s56, 0x21280b00
	s_addc_u32 s21, s57, 0
	s_add_u32 s22, s56, 0x21280c00
	s_addc_u32 s23, s57, 0
	s_add_u32 s24, s56, 0x21280d00
	s_addc_u32 s25, s57, 0
	s_add_u32 s26, s56, 0x21280e00
	s_addc_u32 s27, s57, 0
	s_add_u32 s28, s56, 0x21280f00
	s_addc_u32 s29, s57, 0
	s_add_u32 s30, s56, 0x21281000
	s_addc_u32 s31, s57, 0
	s_add_u32 s34, s56, 0x21281100
	s_addc_u32 s35, s57, 0
	s_add_u32 s36, s56, 0x21281200
	s_addc_u32 s37, s57, 0
	s_mul_i32 s33, s91, s85
	s_add_u32 s38, s56, 0x21281300
	s_mul_i32 s33, s33, s90
	s_addc_u32 s39, s57, 0
	s_mov_b32 s46, 1
	v_mov_b32_e32 v16, 0
	s_branch .LBB0_877

.LBB0_932:
	s_ashr_i32 s2, s1, 3
	s_add_u32 s36, s56, 0x4300000
	s_addc_u32 s37, s57, 0
	s_add_u32 s38, s56, 0x8100000
	s_addc_u32 s39, s57, 0
	s_add_i32 s2, s8, s2
	s_ashr_i32 s8, s2, 31
	s_lshr_b32 s8, s8, 26
	s_add_i32 s8, s2, s8
	s_ashr_i32 s9, s8, 6
	s_and_b32 s8, s8, 0xffc0
	s_sub_i32 s8, s2, s8
	s_bfe_i32 s2, s8, 0x80000
	s_bfe_u32 s2, s2, 0x3000c
	s_add_i32 s10, s8, s2
	s_bfe_i32 s2, s10, 0x80000
	s_and_b32 s10, s10, 0xf8
	s_sub_i32 s8, s8, s10
	s_lshl_b32 s9, s9, 3
	s_sext_i32_i8 s8, s8
	s_ashr_i32 s1, s0, 31
	s_add_i32 s62, s9, s8
	s_lshl_b64 s[4:5], s[0:1], 9
	s_ashr_i32 s8, s62, 31
	s_mul_i32 s8, s4, s8
	s_mul_hi_u32 s9, s4, s62
	s_sext_i32_i16 s12, s2
	s_add_i32 s10, s9, s8
	s_lshr_b64 s[8:9], s[0:1], 23
	s_lshr_b32 s3, s18, 8
	s_lshr_b32 s2, s12, 3
	s_mul_i32 s9, s8, s62
	s_add_i32 s13, s10, s9
	s_bfe_i64 s[10:11], s[2:3], 0x100000
	s_ashr_i32 s9, s12, 3
	s_mul_hi_u32 s10, s4, s9
	s_mul_i32 s11, s4, s11
	s_lshr_b32 s16, s18, 6
	s_add_i32 s10, s10, s11
	s_mul_i32 s8, s8, s9
	s_lshl_b64 s[6:7], s[0:1], 8
	s_lshl_b32 s40, s16, 10
	s_add_i32 s10, s10, s8
	s_mul_i32 s8, s4, s9
	v_mul_lo_u32 v0, s0, v149
	s_add_u32 s34, s38, s8
	v_add_lshl_u32 v128, v0, v148, 1
	v_mul_lo_u32 v0, s0, v150
	s_addc_u32 s35, s39, s10
	s_add_i32 s41, s40, 0
	v_add_lshl_u32 v130, v0, v148, 1
	v_mul_lo_u32 v0, s0, v151
	s_add_i32 m0, s41, 0x10000
	v_add_lshl_u32 v132, v0, v148, 1
	v_mul_lo_u32 v0, s0, v152
	global_load_lds_dwordx4 v130, s[34:35]
	s_add_i32 m0, s41, 0x12000
	v_add_lshl_u32 v134, v0, v148, 1
	s_add_u32 s8, s34, s6
	global_load_lds_dwordx4 v134, s[34:35]
	s_addc_u32 s9, s35, s7
	s_add_i32 m0, s41, 0x14000
	s_mul_i32 s17, s4, s62
	global_load_lds_dwordx4 v130, s[8:9]
	s_add_i32 m0, s41, 0x16000
	s_add_u32 s30, s36, s17
	s_addc_u32 s31, s37, s13
	s_add_i32 s42, s41, 0x2000
	global_load_lds_dwordx4 v134, s[8:9]
	s_mov_b32 m0, s41
	s_add_u32 s10, s30, s6
	global_load_lds_dwordx4 v128, s[30:31]
	s_mov_b32 m0, s42
	s_addc_u32 s11, s31, s7
	s_add_i32 s43, s41, 0x4000
	global_load_lds_dwordx4 v132, s[30:31]
	s_mov_b32 m0, s43
	s_add_i32 s44, s41, 0x6000
	global_load_lds_dwordx4 v128, s[10:11]
	s_mov_b32 m0, s44
	v_mov_b32_e32 v131, 0
	global_load_lds_dwordx4 v132, s[10:11]
	v_mov_b32_e32 v135, v131
	v_mov_b32_e32 v129, v131
	v_mov_b32_e32 v133, v131
	s_cmp_eq_u32 s3, 1
	s_mov_b32 s45, 0
	v_lshl_add_u64 v[8:9], s[34:35], 0, v[130:131]
	v_lshl_add_u64 v[4:5], s[34:35], 0, v[134:135]
	v_lshl_add_u64 v[2:3], s[8:9], 0, v[130:131]
	v_lshl_add_u64 v[0:1], s[8:9], 0, v[134:135]
	v_lshl_add_u64 v[6:7], s[30:31], 0, v[128:129]
	s_cselect_b64 s[8:9], -1, 0
	s_cmp_lg_u32 s3, 1
	v_lshl_add_u64 v[10:11], s[30:31], 0, v[132:133]
	s_cbranch_scc1 .LBB0_934
	s_setprio 1
	s_barrier

.LBB0_956:
	v_readfirstlane_b32 s3, v220
	s_movk_i32 s0, 0x800
	s_cmpk_gt_i32 s84, 0xaff
	s_cbranch_scc1 .LBB0_977
	s_add_u32 s33, s56, 0x8200000
	s_addc_u32 s36, s57, 0
	s_add_u32 s37, s56, 0x100000
	s_addc_u32 s38, s57, 0
	s_ashr_i32 s40, s84, 31
	s_lshr_b32 s2, s40, 29
	s_add_i32 s2, s84, s2
	s_lshr_b32 s8, s3, 6
	s_ashr_i32 s1, s0, 31
	s_ashr_i32 s4, s2, 3
	s_and_b32 s2, s2, -8
	s_lshr_b32 s9, s3, 8
	s_lshl_b64 s[16:17], s[0:1], 9
	s_lshl_b64 s[18:19], s[0:1], 8
	s_lshl_b32 s39, s8, 10
	s_sub_i32 s2, s84, s2
	s_cmp_lt_i32 s2, 0
	s_movk_i32 s41, 0x161
	s_cselect_b32 s5, s41, 0x160
	s_mul_i32 s2, s2, s5
	s_add_i32 s2, s2, s4
	s_mul_hi_i32 s4, s2, 0x2e8ba2e9
	s_lshr_b32 s5, s4, 31
	s_ashr_i32 s4, s4, 6
	s_add_i32 s4, s4, s5
	s_lshl_b32 s5, s4, 3
	s_mulk_i32 s4, 0x160
	s_sub_i32 s4, s2, s4
	s_bfe_u32 s2, s4, 0x3001c
	s_add_i32 s6, s4, s2
	s_sext_i32_i16 s10, s6
	s_and_b32 s6, s6, 0xfff8
	s_sub_i32 s4, s4, s6
	s_sext_i32_i16 s4, s4
	s_add_i32 s65, s5, s4
	s_ashr_i32 s4, s65, 31
	s_mul_i32 s4, s16, s4
	s_mul_hi_u32 s5, s16, s65
	s_add_i32 s6, s5, s4
	s_lshr_b64 s[4:5], s[0:1], 23
	s_lshr_b32 s2, s10, 3
	s_mul_i32 s5, s4, s65
	s_add_i32 s12, s6, s5
	s_bfe_i64 s[6:7], s[2:3], 0x100000
	s_ashr_i32 s5, s10, 3
	s_mul_hi_u32 s6, s16, s5
	s_mul_i32 s7, s16, s7
	s_add_i32 s6, s6, s7
	s_mul_i32 s4, s4, s5
	v_mul_lo_u32 v0, s0, v152
	s_add_i32 s6, s6, s4
	s_mul_i32 s4, s16, s5
	v_add_lshl_u32 v128, v0, v148, 1
	v_mul_lo_u32 v0, s0, v151
	s_add_u32 s4, s37, s4
	v_add_lshl_u32 v130, v0, v148, 1
	v_mul_lo_u32 v0, s0, v150
	s_addc_u32 s5, s38, s6
	s_add_i32 s42, s39, 0
	v_add_lshl_u32 v132, v0, v148, 1
	s_add_i32 m0, s42, 0x10000
	s_mul_i32 s13, s16, s65
	global_load_lds_dwordx4 v132, s[4:5]
	s_add_i32 m0, s42, 0x12000
	s_add_u32 s10, s4, s18
	global_load_lds_dwordx4 v128, s[4:5]
	s_addc_u32 s11, s5, s19
	s_add_i32 m0, s42, 0x14000
	v_mul_lo_u32 v0, s0, v149
	global_load_lds_dwordx4 v132, s[10:11]
	s_add_i32 m0, s42, 0x16000
	s_add_u32 s6, s33, s13
	s_addc_u32 s7, s36, s12
	s_add_i32 s43, s42, 0x2000
	v_add_lshl_u32 v134, v0, v148, 1
	global_load_lds_dwordx4 v128, s[10:11]
	s_mov_b32 m0, s42
	s_add_u32 s12, s6, s18
	global_load_lds_dwordx4 v134, s[6:7]
	s_mov_b32 m0, s43
	s_addc_u32 s13, s7, s19
	s_add_i32 s44, s42, 0x4000
	global_load_lds_dwordx4 v130, s[6:7]
	s_mov_b32 m0, s44
	s_add_i32 s45, s42, 0x6000
	global_load_lds_dwordx4 v134, s[12:13]
	s_mov_b32 m0, s45
	v_mov_b32_e32 v137, 0
	global_load_lds_dwordx4 v130, s[12:13]
	v_mov_b32_e32 v133, v137
	v_mov_b32_e32 v129, v137
	v_mov_b32_e32 v135, v137
	v_mov_b32_e32 v131, v137
	s_cmp_eq_u32 s9, 1
	s_mov_b32 s46, 0
	v_lshl_add_u64 v[8:9], s[4:5], 0, v[132:133]
	v_lshl_add_u64 v[4:5], s[4:5], 0, v[128:129]
	v_lshl_add_u64 v[2:3], s[10:11], 0, v[132:133]
	v_lshl_add_u64 v[0:1], s[10:11], 0, v[128:129]
	v_lshl_add_u64 v[6:7], s[6:7], 0, v[134:135]
	s_cselect_b64 s[20:21], -1, 0
	s_cmp_lg_u32 s9, 1
	v_lshl_add_u64 v[10:11], s[6:7], 0, v[130:131]
	s_cbranch_scc1 .LBB0_959
	s_setprio 1
	s_barrier

.LBB0_977:
	s_setprio 0
	s_cmp_gt_i32 s59, 10
	s_cselect_b64 s[0:1], -1, 0
	s_and_b64 s[2:3], s[14:15], s[0:1]
	s_andn2_b64 vcc, exec, s[2:3]
	s_cbranch_vccnz .LBB0_1031
	s_waitcnt vmcnt(0) lgkmcnt(0)
	s_waitcnt vmcnt(0)
	s_waitcnt vmcnt(0) lgkmcnt(0)
	s_barrier
	s_and_saveexec_b64 s[2:3], s[92:93]
	s_cbranch_execz .LBB0_1030
	s_add_i32 s4, 0, 0x23fc0
	v_mov_b32_e32 v0, s4
	s_waitcnt vmcnt(0) expcnt(0) lgkmcnt(0)
	ds_read_b32 v2, v0
	s_add_i32 s4, 0, 0x23fc4
	v_mov_b32_e32 v0, s4
	ds_read_b32 v0, v0
	s_waitcnt lgkmcnt(1)
	v_cmp_ne_u32_e32 vcc, 0, v2
	s_cbranch_vccnz .LBB0_994
	s_add_u32 s4, s56, 0x21280200
	s_addc_u32 s5, s57, 0
	s_add_u32 s6, s56, 0x21280400
	s_addc_u32 s7, s57, 0
	s_add_u32 s8, s56, 0x21280500
	s_addc_u32 s9, s57, 0
	s_add_u32 s10, s56, 0x21280600
	s_addc_u32 s11, s57, 0
	s_add_u32 s12, s56, 0x21280700
	s_addc_u32 s13, s57, 0
	s_add_u32 s14, s56, 0x21280800
	s_addc_u32 s15, s57, 0
	s_add_u32 s16, s56, 0x21280900
	s_addc_u32 s17, s57, 0
	s_add_u32 s18, s56, 0x21280a00
	s_addc_u32 s19, s57, 0
	s_add_u32 s20, s56, 0x21280b00
	s_addc_u32 s21, s57, 0
	s_add_u32 s22, s56, 0x21280c00
	s_addc_u32 s23, s57, 0
	s_add_u32 s24, s56, 0x21280d00
	s_addc_u32 s25, s57, 0
	s_add_u32 s26, s56, 0x21280e00
	s_addc_u32 s27, s57, 0
	s_add_u32 s28, s56, 0x21280f00
	s_addc_u32 s29, s57, 0
	s_add_u32 s30, s56, 0x21281000
	s_addc_u32 s31, s57, 0
	s_add_u32 s34, s56, 0x21281100
	s_addc_u32 s35, s57, 0
	s_add_u32 s36, s56, 0x21281200
	s_addc_u32 s37, s57, 0
	s_mul_i32 s33, s91, s85
	s_add_u32 s38, s56, 0x21281300
	s_mul_i32 s33, s33, s90
	s_addc_u32 s39, s57, 0
	s_mov_b32 s46, 1
	v_mov_b32_e32 v16, 0
	s_branch .LBB0_982

.LBB0_1038:
	s_andn2_b64 vcc, exec, s[2:3]
	s_cbranch_vccnz .LBB0_1080
	s_add_u32 s33, s56, 0xc200000
	s_addc_u32 s34, s57, 0
	s_add_u32 s35, s56, 0x2d00000
	s_addc_u32 s36, s57, 0
	s_ashr_i32 s1, s0, 31
	s_lshl_b64 s[8:9], s[0:1], 9
	s_ashr_i32 s4, s54, 31
	s_mul_i32 s4, s8, s4
	s_mul_hi_u32 s5, s8, s54
	s_add_i32 s10, s5, s4
	s_lshr_b64 s[4:5], s[0:1], 23
	s_mul_i32 s5, s4, s54
	s_add_i32 s10, s10, s5
	s_ashr_i32 s5, s55, 31
	s_mul_i32 s5, s8, s5
	s_mul_hi_u32 s12, s8, s55
	s_lshr_b32 s3, s18, 6
	s_add_i32 s5, s12, s5
	s_mul_i32 s4, s4, s55
	s_lshr_b32 s2, s18, 8
	v_lshlrev_b32_e32 v3, 4, v220
	v_and_b32_e32 v0, 32, v220
	v_lshlrev_b32_e32 v2, 5, v220
	s_lshl_b32 s37, s3, 10
	s_add_i32 s5, s5, s4
	s_mul_i32 s4, s8, s55
	v_bitop3_b32 v0, v3, v0, 48 bitop3:0x6c
	s_waitcnt lgkmcnt(0)
	v_and_b32_e32 v1, 64, v220
	v_and_b32_e32 v2, 0x780, v2
	s_add_u32 s26, s35, s4
	v_or3_b32 v5, v2, v1, v0
	v_and_b32_e32 v4, 0x3800, v3
	s_addc_u32 s27, s36, s5
	s_add_i32 s38, s37, 0
	v_or_b32_e32 v128, v5, v4
	v_add_u32_e32 v3, 0x2000, v3
	s_add_i32 m0, s38, 0x10000
	v_and_b32_e32 v3, 0x7800, v3
	global_load_lds_dwordx4 v128, s[26:27]
	s_add_i32 m0, s38, 0x12000
	v_or_b32_e32 v130, v5, v3
	s_add_u32 s4, s26, 0x4000
	global_load_lds_dwordx4 v130, s[26:27]
	s_addc_u32 s5, s27, 0
	s_add_i32 m0, s38, 0x14000
	s_mul_i32 s11, s8, s54
	global_load_lds_dwordx4 v128, s[4:5]
	s_add_i32 m0, s38, 0x16000
	s_add_u32 s24, s33, s11
	s_addc_u32 s25, s34, s10
	s_add_i32 s39, s38, 0x2000
	global_load_lds_dwordx4 v130, s[4:5]
	s_mov_b32 m0, s38
	s_add_u32 s4, s24, 0x4000
	global_load_lds_dwordx4 v128, s[24:25]
	s_mov_b32 m0, s39
	s_addc_u32 s5, s25, 0
	s_add_i32 s40, s38, 0x4000
	global_load_lds_dwordx4 v130, s[24:25]
	s_mov_b32 m0, s40
	s_add_i32 s41, s38, 0x6000
	global_load_lds_dwordx4 v128, s[4:5]
	s_mov_b32 m0, s41
	v_mov_b32_e32 v129, 0
	global_load_lds_dwordx4 v130, s[4:5]
	s_cmp_eq_u32 s2, 1
	s_mov_b32 s42, 0
	s_cselect_b64 s[10:11], -1, 0
	s_cmp_lg_u32 s2, 1
	v_mov_b32_e32 v131, v129
	s_cbranch_scc1 .LBB0_1041
	s_setprio 1
	s_barrier

.LBB0_1080:
	s_setprio 0
	s_cmp_gt_i32 s59, 11
	s_cselect_b64 s[0:1], -1, 0
	s_and_b64 s[2:3], s[6:7], s[0:1]
	s_andn2_b64 vcc, exec, s[2:3]
	s_cbranch_vccnz .LBB0_1134
	s_waitcnt vmcnt(0) lgkmcnt(0)
	s_waitcnt vmcnt(0)
	s_waitcnt vmcnt(0) lgkmcnt(0)
	s_barrier
	s_and_saveexec_b64 s[2:3], s[92:93]
	s_cbranch_execz .LBB0_1133
	s_add_i32 s4, 0, 0x23fc0
	v_mov_b32_e32 v0, s4
	s_waitcnt vmcnt(0) expcnt(0) lgkmcnt(0)
	ds_read_b32 v2, v0
	s_add_i32 s4, 0, 0x23fc4
	v_mov_b32_e32 v0, s4
	ds_read_b32 v0, v0
	s_waitcnt lgkmcnt(1)
	v_cmp_ne_u32_e32 vcc, 0, v2
	s_cbranch_vccnz .LBB0_1097
	s_add_u32 s4, s56, 0x21280200
	s_addc_u32 s5, s57, 0
	s_add_u32 s6, s56, 0x21280400
	s_addc_u32 s7, s57, 0
	s_add_u32 s8, s56, 0x21280500
	s_addc_u32 s9, s57, 0
	s_add_u32 s10, s56, 0x21280600
	s_addc_u32 s11, s57, 0
	s_add_u32 s12, s56, 0x21280700
	s_addc_u32 s13, s57, 0
	s_add_u32 s14, s56, 0x21280800
	s_addc_u32 s15, s57, 0
	s_add_u32 s16, s56, 0x21280900
	s_addc_u32 s17, s57, 0
	s_add_u32 s18, s56, 0x21280a00
	s_addc_u32 s19, s57, 0
	s_add_u32 s20, s56, 0x21280b00
	s_addc_u32 s21, s57, 0
	s_add_u32 s22, s56, 0x21280c00
	s_addc_u32 s23, s57, 0
	s_add_u32 s24, s56, 0x21280d00
	s_addc_u32 s25, s57, 0
	s_add_u32 s26, s56, 0x21280e00
	s_addc_u32 s27, s57, 0
	s_add_u32 s28, s56, 0x21280f00
	s_addc_u32 s29, s57, 0
	s_add_u32 s30, s56, 0x21281000
	s_addc_u32 s31, s57, 0
	s_add_u32 s34, s56, 0x21281100
	s_addc_u32 s35, s57, 0
	s_add_u32 s36, s56, 0x21281200
	s_addc_u32 s37, s57, 0
	s_mul_i32 s33, s91, s85
	s_add_u32 s38, s56, 0x21281300
	s_mul_i32 s33, s33, s90
	s_addc_u32 s39, s57, 0
	s_mov_b32 s46, 1
	v_mov_b32_e32 v16, 0
	s_branch .LBB0_1085

.LBB0_1141:
	s_andn2_b64 vcc, exec, s[2:3]
	s_cbranch_vccnz .LBB0_1199
	s_add_u32 s42, s56, 0x8200000
	s_addc_u32 s43, s57, 0
	s_waitcnt lgkmcnt(0)
	v_lshlrev_b32_e32 v1, 4, v220
	v_and_b32_e32 v0, 32, v220
	v_lshrrev_b32_e32 v2, 3, v220
	s_add_u32 s44, s56, 0x7900000
	v_bfe_u32 v14, v220, 2, 4
	v_bitop3_b32 v12, v1, v0, 48 bitop3:0x6c
	v_and_b32_e32 v13, 64, v220
	v_and_b32_e32 v16, 0x70, v2
	s_addc_u32 s45, s57, 0
	v_or_b32_e32 v0, v12, v13
	s_lshl_b32 s1, s0, 1
	v_or_b32_e32 v2, v16, v14
	v_mad_u64_u32 v[148:149], s[4:5], s1, v2, v[0:1]
	v_add_u32_e32 v1, 0x2000, v1
	v_lshrrev_b32_e32 v1, 7, v1
	v_and_b32_e32 v15, 0xf0, v1
	v_or_b32_e32 v1, v15, v14
	v_mad_u64_u32 v[150:151], s[4:5], s1, v1, v[0:1]
	s_ashr_i32 s1, s0, 31
	s_lshl_b64 s[8:9], s[0:1], 9
	s_ashr_i32 s4, s33, 31
	s_mul_i32 s4, s8, s4
	s_mul_hi_u32 s5, s8, s33
	s_add_i32 s6, s5, s4
	s_lshr_b64 s[4:5], s[0:1], 23
	s_mul_i32 s5, s4, s33
	s_add_i32 s12, s6, s5
	s_ashr_i32 s5, s40, 31
	s_mul_i32 s5, s8, s5
	s_mul_hi_u32 s6, s8, s40
	s_lshr_b32 s3, s24, 6
	s_add_i32 s5, s6, s5
	s_mul_i32 s4, s4, s40
	s_lshr_b32 s2, s24, 8
	s_lshl_b64 s[10:11], s[0:1], 8
	s_lshl_b32 s46, s3, 10
	s_add_i32 s5, s5, s4
	s_mul_i32 s4, s8, s40
	s_add_u32 s6, s44, s4
	s_addc_u32 s7, s45, s5
	s_add_i32 s47, s46, 0
	s_add_i32 m0, s47, 0x10000
	s_mul_i32 s13, s8, s33
	global_load_lds_dwordx4 v148, s[6:7]
	s_add_i32 m0, s47, 0x12000
	s_add_u32 s4, s6, s10
	global_load_lds_dwordx4 v150, s[6:7]
	s_addc_u32 s5, s7, s11
	s_add_i32 m0, s47, 0x14000
	v_mov_b32_e32 v149, 0
	global_load_lds_dwordx4 v148, s[4:5]
	s_add_i32 m0, s47, 0x16000
	s_add_u32 s38, s42, s13
	s_addc_u32 s39, s43, s12
	s_add_i32 s48, s47, 0x2000
	global_load_lds_dwordx4 v150, s[4:5]
	s_mov_b32 m0, s47
	s_add_u32 s12, s38, s10
	global_load_lds_dwordx4 v148, s[38:39]
	s_mov_b32 m0, s48
	s_addc_u32 s13, s39, s11
	s_add_i32 s49, s47, 0x4000
	global_load_lds_dwordx4 v150, s[38:39]
	s_mov_b32 m0, s49
	s_add_i32 s50, s47, 0x6000
	global_load_lds_dwordx4 v148, s[12:13]
	s_mov_b32 m0, s50
	v_mov_b32_e32 v151, v149
	global_load_lds_dwordx4 v150, s[12:13]
	s_cmp_eq_u32 s2, 1
	s_mov_b32 s51, 0
	v_lshl_add_u64 v[10:11], s[6:7], 0, v[148:149]
	v_lshl_add_u64 v[8:9], s[6:7], 0, v[150:151]
	v_lshl_add_u64 v[2:3], s[4:5], 0, v[148:149]
	v_lshl_add_u64 v[0:1], s[4:5], 0, v[150:151]
	v_lshl_add_u64 v[4:5], s[38:39], 0, v[148:149]
	s_cselect_b64 s[12:13], -1, 0
	s_cmp_lg_u32 s2, 1
	v_lshl_add_u64 v[6:7], s[38:39], 0, v[150:151]
	s_cbranch_scc1 .LBB0_1144
	s_setprio 1
	s_barrier

.LBB0_1199:
	s_setprio 0
	s_endpgm
